# v44: v41 + loop back-edge rotation: loop-carried SALU and exit test hoisted above the loop-back barrier in the four hot GEMM K-loops
# speedup vs baseline: 1.0051x; 1.0051x over previous
.LBB0_374:
	ds_read_b128 v[152:155], v157
	ds_read_b128 v[160:163], v157 offset:1024
	ds_read_b128 v[164:167], v157 offset:2048
	ds_read_b128 v[168:171], v157 offset:3072
	ds_read_b128 v[172:175], v158
	ds_read_b128 v[176:179], v158 offset:1024
	ds_read_b128 v[180:183], v158 offset:2048
	ds_read_b128 v[184:187], v158 offset:3072
	s_add_u32 s28, s26, 0xfffc0080
	s_addc_u32 s29, s27, -1
	s_cmp_eq_u32 s80, 12
	s_cselect_b32 s31, s7, s29
	s_cselect_b32 s30, s21, s28
	s_cselect_b32 s29, s19, s59
	s_cselect_b32 s28, s57, s58
	v_lshl_add_u64 v[222:223], s[26:27], 0, v[144:145]
	s_add_i32 m0, s9, 0xc000
	ds_read_b128 v[188:191], v159
	ds_read_b128 v[192:195], v159 offset:1024
	ds_read_b128 v[196:199], v159 offset:2048
	ds_read_b128 v[200:203], v159 offset:3072
	ds_read_b128 v[204:207], v159 offset:4096
	ds_read_b128 v[210:213], v159 offset:5120
	ds_read_b128 v[214:217], v159 offset:6144
	ds_read_b128 v[218:221], v159 offset:7168
	global_load_lds_dwordx4 v[222:223], off
	v_lshl_add_u64 v[222:223], s[26:27], 0, v[146:147]
	s_add_i32 m0, s9, 0xe000
	s_nop 0
	global_load_lds_dwordx4 v[222:223], off
	s_waitcnt vmcnt(8)
	s_waitcnt lgkmcnt(0)
	s_barrier
	s_setprio 1
	s_waitcnt lgkmcnt(0)
	v_mfma_f32_16x16x32_bf16 v[126:129], v[152:155], v[188:191], v[126:129]
	v_mfma_f32_16x16x32_bf16 v[122:125], v[164:167], v[188:191], v[122:125]
	v_mfma_f32_16x16x32_bf16 v[110:113], v[152:155], v[196:199], v[110:113]
	v_mfma_f32_16x16x32_bf16 v[106:109], v[164:167], v[196:199], v[106:109]
	v_mfma_f32_16x16x32_bf16 v[94:97], v[152:155], v[204:207], v[94:97]
	v_mfma_f32_16x16x32_bf16 v[90:93], v[164:167], v[204:207], v[90:93]
	v_mfma_f32_16x16x32_bf16 v[78:81], v[152:155], v[214:217], v[78:81]
	v_mfma_f32_16x16x32_bf16 v[74:77], v[164:167], v[214:217], v[74:77]
	v_mfma_f32_16x16x32_bf16 v[126:129], v[160:163], v[192:195], v[126:129]
	v_mfma_f32_16x16x32_bf16 v[122:125], v[168:171], v[192:195], v[122:125]
	v_mfma_f32_16x16x32_bf16 v[110:113], v[160:163], v[200:203], v[110:113]
	v_mfma_f32_16x16x32_bf16 v[106:109], v[168:171], v[200:203], v[106:109]
	v_mfma_f32_16x16x32_bf16 v[94:97], v[160:163], v[210:213], v[94:97]
	v_mfma_f32_16x16x32_bf16 v[90:93], v[168:171], v[210:213], v[90:93]
	v_mfma_f32_16x16x32_bf16 v[78:81], v[160:163], v[218:221], v[78:81]
	v_mfma_f32_16x16x32_bf16 v[74:77], v[168:171], v[218:221], v[74:77]
	s_setprio 0
	s_setprio 1
	v_mfma_f32_16x16x32_bf16 v[118:121], v[172:175], v[188:191], v[118:121]
	v_mfma_f32_16x16x32_bf16 v[114:117], v[180:183], v[188:191], v[114:117]
	v_mfma_f32_16x16x32_bf16 v[102:105], v[172:175], v[196:199], v[102:105]
	v_mfma_f32_16x16x32_bf16 v[98:101], v[180:183], v[196:199], v[98:101]
	v_mfma_f32_16x16x32_bf16 v[86:89], v[172:175], v[204:207], v[86:89]
	v_mfma_f32_16x16x32_bf16 v[82:85], v[180:183], v[204:207], v[82:85]
	v_mfma_f32_16x16x32_bf16 v[70:73], v[172:175], v[214:217], v[70:73]
	v_mfma_f32_16x16x32_bf16 v[66:69], v[180:183], v[214:217], v[66:69]
	v_mfma_f32_16x16x32_bf16 v[118:121], v[176:179], v[192:195], v[118:121]
	v_mfma_f32_16x16x32_bf16 v[114:117], v[184:187], v[192:195], v[114:117]
	v_mfma_f32_16x16x32_bf16 v[102:105], v[176:179], v[200:203], v[102:105]
	v_mfma_f32_16x16x32_bf16 v[98:101], v[184:187], v[200:203], v[98:101]
	v_mfma_f32_16x16x32_bf16 v[86:89], v[176:179], v[210:213], v[86:89]
	v_mfma_f32_16x16x32_bf16 v[82:85], v[184:187], v[210:213], v[82:85]
	v_mfma_f32_16x16x32_bf16 v[70:73], v[176:179], v[218:221], v[70:73]
	v_mfma_f32_16x16x32_bf16 v[66:69], v[184:187], v[218:221], v[66:69]
	s_setprio 0
	s_barrier
	s_add_i32 s81, s44, s35
	v_lshl_add_u64 v[222:223], s[28:29], 0, v[132:133]
	s_mov_b32 m0, s81
	ds_read_b128 v[188:191], v159 offset:16384
	ds_read_b128 v[192:195], v159 offset:17408
	ds_read_b128 v[196:199], v159 offset:18432
	ds_read_b128 v[200:203], v159 offset:19456
	ds_read_b128 v[204:207], v159 offset:20480
	ds_read_b128 v[210:213], v159 offset:21504
	ds_read_b128 v[214:217], v159 offset:22528
	ds_read_b128 v[218:221], v159 offset:23552
	global_load_lds_dwordx4 v[222:223], off
	s_add_i32 m0, s81, 0x2000
	s_add_u32 s82, s28, 0x40000
	v_lshl_add_u64 v[224:225], s[28:29], 0, v[136:137]
	s_addc_u32 s83, s29, 0
	s_add_i32 s81, s45, s35
	global_load_lds_dwordx4 v[224:225], off
	v_lshl_add_u64 v[226:227], s[82:83], 0, v[132:133]
	s_mov_b32 m0, s81
	v_lshl_add_u64 v[228:229], s[30:31], 0, v[134:135]
	global_load_lds_dwordx4 v[226:227], off
	v_lshl_add_u64 v[226:227], s[82:83], 0, v[136:137]
	s_add_i32 m0, s81, 0x2000
	s_nop 0
	global_load_lds_dwordx4 v[226:227], off
	v_lshl_add_u64 v[226:227], s[30:31], 0, v[130:131]
	s_mov_b32 m0, s9
	s_nop 0
	global_load_lds_dwordx4 v[226:227], off
	s_mov_b32 m0, s36
	s_nop 0
	global_load_lds_dwordx4 v[228:229], off
	s_waitcnt vmcnt(8)
	s_waitcnt lgkmcnt(0)
	s_barrier
	s_setprio 1
	s_waitcnt lgkmcnt(0)
	v_mfma_f32_16x16x32_bf16 v[62:65], v[152:155], v[188:191], v[62:65]
	v_mfma_f32_16x16x32_bf16 v[58:61], v[164:167], v[188:191], v[58:61]
	v_mfma_f32_16x16x32_bf16 v[46:49], v[152:155], v[196:199], v[46:49]
	v_mfma_f32_16x16x32_bf16 v[42:45], v[164:167], v[196:199], v[42:45]
	v_mfma_f32_16x16x32_bf16 v[30:33], v[152:155], v[204:207], v[30:33]
	v_mfma_f32_16x16x32_bf16 v[26:29], v[164:167], v[204:207], v[26:29]
	v_mfma_f32_16x16x32_bf16 v[14:17], v[152:155], v[214:217], v[14:17]
	v_mfma_f32_16x16x32_bf16 v[10:13], v[164:167], v[214:217], v[10:13]
	v_mfma_f32_16x16x32_bf16 v[62:65], v[160:163], v[192:195], v[62:65]
	v_mfma_f32_16x16x32_bf16 v[58:61], v[168:171], v[192:195], v[58:61]
	v_mfma_f32_16x16x32_bf16 v[46:49], v[160:163], v[200:203], v[46:49]
	v_mfma_f32_16x16x32_bf16 v[42:45], v[168:171], v[200:203], v[42:45]
	v_mfma_f32_16x16x32_bf16 v[30:33], v[160:163], v[210:213], v[30:33]
	v_mfma_f32_16x16x32_bf16 v[26:29], v[168:171], v[210:213], v[26:29]
	v_mfma_f32_16x16x32_bf16 v[14:17], v[160:163], v[218:221], v[14:17]
	v_mfma_f32_16x16x32_bf16 v[10:13], v[168:171], v[218:221], v[10:13]
	s_setprio 0
	s_setprio 1
	v_mfma_f32_16x16x32_bf16 v[54:57], v[172:175], v[188:191], v[54:57]
	v_mfma_f32_16x16x32_bf16 v[50:53], v[180:183], v[188:191], v[50:53]
	v_mfma_f32_16x16x32_bf16 v[38:41], v[172:175], v[196:199], v[38:41]
	v_mfma_f32_16x16x32_bf16 v[34:37], v[180:183], v[196:199], v[34:37]
	v_mfma_f32_16x16x32_bf16 v[22:25], v[172:175], v[204:207], v[22:25]
	v_mfma_f32_16x16x32_bf16 v[18:21], v[180:183], v[204:207], v[18:21]
	v_mfma_f32_16x16x32_bf16 v[6:9], v[172:175], v[214:217], v[6:9]
	v_mfma_f32_16x16x32_bf16 v[2:5], v[180:183], v[214:217], v[2:5]
	v_mfma_f32_16x16x32_bf16 v[54:57], v[176:179], v[192:195], v[54:57]
	v_mfma_f32_16x16x32_bf16 v[50:53], v[184:187], v[192:195], v[50:53]
	v_mfma_f32_16x16x32_bf16 v[38:41], v[176:179], v[200:203], v[38:41]
	v_mfma_f32_16x16x32_bf16 v[34:37], v[184:187], v[200:203], v[34:37]
	v_mfma_f32_16x16x32_bf16 v[22:25], v[176:179], v[210:213], v[22:25]
	v_mfma_f32_16x16x32_bf16 v[18:21], v[184:187], v[210:213], v[18:21]
	v_mfma_f32_16x16x32_bf16 v[6:9], v[176:179], v[218:221], v[6:9]
	v_mfma_f32_16x16x32_bf16 v[2:5], v[184:187], v[218:221], v[2:5]
	s_setprio 0
	s_barrier
	s_add_i32 s81, 0, 0x18000
	v_add_u32_e32 v138, s81, v156
	s_add_i32 s82, 0, 0x1c000
	ds_read_b128 v[152:155], v138
	ds_read_b128 v[160:163], v138 offset:1024
	ds_read_b128 v[164:167], v138 offset:2048
	ds_read_b128 v[168:171], v138 offset:3072
	v_add_u32_e32 v138, 0x1000, v138
	ds_read_b128 v[172:175], v138
	ds_read_b128 v[176:179], v138 offset:1024
	ds_read_b128 v[180:183], v138 offset:2048
	ds_read_b128 v[184:187], v138 offset:3072
	s_add_u32 s30, s30, 0x40000
	s_addc_u32 s31, s31, 0
	s_mov_b32 m0, s37
	v_lshl_add_u64 v[230:231], s[30:31], 0, v[130:131]
	ds_read_b128 v[188:191], v159 offset:32768
	ds_read_b128 v[192:195], v159 offset:33792
	ds_read_b128 v[196:199], v159 offset:34816
	ds_read_b128 v[200:203], v159 offset:35840
	ds_read_b128 v[204:207], v159 offset:36864
	ds_read_b128 v[210:213], v159 offset:37888
	ds_read_b128 v[214:217], v159 offset:38912
	ds_read_b128 v[218:221], v159 offset:39936
	global_load_lds_dwordx4 v[230:231], off
	v_lshl_add_u64 v[230:231], s[30:31], 0, v[134:135]
	s_mov_b32 m0, s38
	s_nop 0
	global_load_lds_dwordx4 v[230:231], off
	s_waitcnt vmcnt(8)
	s_waitcnt lgkmcnt(0)
	s_barrier
	s_setprio 1
	s_waitcnt lgkmcnt(0)
	v_mfma_f32_16x16x32_bf16 v[126:129], v[152:155], v[188:191], v[126:129]
	v_mfma_f32_16x16x32_bf16 v[122:125], v[164:167], v[188:191], v[122:125]
	v_mfma_f32_16x16x32_bf16 v[110:113], v[152:155], v[196:199], v[110:113]
	v_mfma_f32_16x16x32_bf16 v[106:109], v[164:167], v[196:199], v[106:109]
	v_mfma_f32_16x16x32_bf16 v[94:97], v[152:155], v[204:207], v[94:97]
	v_mfma_f32_16x16x32_bf16 v[90:93], v[164:167], v[204:207], v[90:93]
	v_mfma_f32_16x16x32_bf16 v[78:81], v[152:155], v[214:217], v[78:81]
	v_mfma_f32_16x16x32_bf16 v[74:77], v[164:167], v[214:217], v[74:77]
	v_mfma_f32_16x16x32_bf16 v[126:129], v[160:163], v[192:195], v[126:129]
	v_mfma_f32_16x16x32_bf16 v[122:125], v[168:171], v[192:195], v[122:125]
	v_mfma_f32_16x16x32_bf16 v[110:113], v[160:163], v[200:203], v[110:113]
	v_mfma_f32_16x16x32_bf16 v[106:109], v[168:171], v[200:203], v[106:109]
	v_mfma_f32_16x16x32_bf16 v[94:97], v[160:163], v[210:213], v[94:97]
	v_mfma_f32_16x16x32_bf16 v[90:93], v[168:171], v[210:213], v[90:93]
	v_mfma_f32_16x16x32_bf16 v[78:81], v[160:163], v[218:221], v[78:81]
	v_mfma_f32_16x16x32_bf16 v[74:77], v[168:171], v[218:221], v[74:77]
	s_setprio 0
	s_setprio 1
	v_mfma_f32_16x16x32_bf16 v[118:121], v[172:175], v[188:191], v[118:121]
	v_mfma_f32_16x16x32_bf16 v[114:117], v[180:183], v[188:191], v[114:117]
	v_mfma_f32_16x16x32_bf16 v[102:105], v[172:175], v[196:199], v[102:105]
	v_mfma_f32_16x16x32_bf16 v[98:101], v[180:183], v[196:199], v[98:101]
	v_mfma_f32_16x16x32_bf16 v[86:89], v[172:175], v[204:207], v[86:89]
	v_mfma_f32_16x16x32_bf16 v[82:85], v[180:183], v[204:207], v[82:85]
	v_mfma_f32_16x16x32_bf16 v[70:73], v[172:175], v[214:217], v[70:73]
	v_mfma_f32_16x16x32_bf16 v[66:69], v[180:183], v[214:217], v[66:69]
	v_mfma_f32_16x16x32_bf16 v[118:121], v[176:179], v[192:195], v[118:121]
	v_mfma_f32_16x16x32_bf16 v[114:117], v[184:187], v[192:195], v[114:117]
	v_mfma_f32_16x16x32_bf16 v[102:105], v[176:179], v[200:203], v[102:105]
	v_mfma_f32_16x16x32_bf16 v[98:101], v[184:187], v[200:203], v[98:101]
	v_mfma_f32_16x16x32_bf16 v[86:89], v[176:179], v[210:213], v[86:89]
	v_mfma_f32_16x16x32_bf16 v[82:85], v[184:187], v[210:213], v[82:85]
	v_mfma_f32_16x16x32_bf16 v[70:73], v[176:179], v[218:221], v[70:73]
	v_mfma_f32_16x16x32_bf16 v[66:69], v[184:187], v[218:221], v[66:69]
	s_setprio 0
	s_barrier
	s_add_i32 s30, s81, s35
	v_lshl_add_u64 v[222:223], v[222:223], 0, s[14:15]
	s_mov_b32 m0, s30
	ds_read_b128 v[188:191], v159 offset:49152
	ds_read_b128 v[192:195], v159 offset:50176
	ds_read_b128 v[196:199], v159 offset:51200
	ds_read_b128 v[200:203], v159 offset:52224
	ds_read_b128 v[204:207], v159 offset:53248
	ds_read_b128 v[210:213], v159 offset:54272
	ds_read_b128 v[214:217], v159 offset:55296
	ds_read_b128 v[218:221], v159 offset:56320
	global_load_lds_dwordx4 v[222:223], off
	s_add_i32 m0, s30, 0x2000
	s_add_u32 s28, s28, 0x40080
	v_lshl_add_u64 v[222:223], v[224:225], 0, s[14:15]
	s_addc_u32 s29, s29, 0
	s_add_i32 s30, s82, s35
	global_load_lds_dwordx4 v[222:223], off
	v_lshl_add_u64 v[222:223], s[28:29], 0, v[132:133]
	s_mov_b32 m0, s30
	s_nop 0
	global_load_lds_dwordx4 v[222:223], off
	v_lshl_add_u64 v[222:223], s[28:29], 0, v[136:137]
	s_add_i32 m0, s30, 0x2000
	s_nop 0
	global_load_lds_dwordx4 v[222:223], off
	v_lshl_add_u64 v[222:223], v[226:227], 0, s[14:15]
	s_mov_b32 m0, s40
	s_nop 0
	global_load_lds_dwordx4 v[222:223], off
	v_lshl_add_u64 v[222:223], v[228:229], 0, s[14:15]
	s_mov_b32 m0, s41
	s_nop 0
	global_load_lds_dwordx4 v[222:223], off
	s_waitcnt vmcnt(8)
	s_waitcnt lgkmcnt(0)
	s_barrier
	s_setprio 1
	s_waitcnt lgkmcnt(0)
	v_mfma_f32_16x16x32_bf16 v[62:65], v[152:155], v[188:191], v[62:65]
	v_mfma_f32_16x16x32_bf16 v[58:61], v[164:167], v[188:191], v[58:61]
	v_mfma_f32_16x16x32_bf16 v[46:49], v[152:155], v[196:199], v[46:49]
	v_mfma_f32_16x16x32_bf16 v[42:45], v[164:167], v[196:199], v[42:45]
	v_mfma_f32_16x16x32_bf16 v[30:33], v[152:155], v[204:207], v[30:33]
	v_mfma_f32_16x16x32_bf16 v[26:29], v[164:167], v[204:207], v[26:29]
	v_mfma_f32_16x16x32_bf16 v[14:17], v[152:155], v[214:217], v[14:17]
	v_mfma_f32_16x16x32_bf16 v[10:13], v[164:167], v[214:217], v[10:13]
	v_mfma_f32_16x16x32_bf16 v[62:65], v[160:163], v[192:195], v[62:65]
	v_mfma_f32_16x16x32_bf16 v[58:61], v[168:171], v[192:195], v[58:61]
	v_mfma_f32_16x16x32_bf16 v[46:49], v[160:163], v[200:203], v[46:49]
	v_mfma_f32_16x16x32_bf16 v[42:45], v[168:171], v[200:203], v[42:45]
	v_mfma_f32_16x16x32_bf16 v[30:33], v[160:163], v[210:213], v[30:33]
	v_mfma_f32_16x16x32_bf16 v[26:29], v[168:171], v[210:213], v[26:29]
	v_mfma_f32_16x16x32_bf16 v[14:17], v[160:163], v[218:221], v[14:17]
	v_mfma_f32_16x16x32_bf16 v[10:13], v[168:171], v[218:221], v[10:13]
	s_setprio 0
	s_setprio 1
	v_mfma_f32_16x16x32_bf16 v[54:57], v[172:175], v[188:191], v[54:57]
	v_mfma_f32_16x16x32_bf16 v[50:53], v[180:183], v[188:191], v[50:53]
	v_mfma_f32_16x16x32_bf16 v[38:41], v[172:175], v[196:199], v[38:41]
	v_mfma_f32_16x16x32_bf16 v[34:37], v[180:183], v[196:199], v[34:37]
	v_mfma_f32_16x16x32_bf16 v[22:25], v[172:175], v[204:207], v[22:25]
	v_mfma_f32_16x16x32_bf16 v[18:21], v[180:183], v[204:207], v[18:21]
	v_mfma_f32_16x16x32_bf16 v[6:9], v[172:175], v[214:217], v[6:9]
	v_mfma_f32_16x16x32_bf16 v[2:5], v[180:183], v[214:217], v[2:5]
	v_mfma_f32_16x16x32_bf16 v[54:57], v[176:179], v[192:195], v[54:57]
	v_mfma_f32_16x16x32_bf16 v[50:53], v[184:187], v[192:195], v[50:53]
	v_mfma_f32_16x16x32_bf16 v[38:41], v[176:179], v[200:203], v[38:41]
	v_mfma_f32_16x16x32_bf16 v[34:37], v[184:187], v[200:203], v[34:37]
	v_mfma_f32_16x16x32_bf16 v[22:25], v[176:179], v[210:213], v[22:25]
	v_mfma_f32_16x16x32_bf16 v[18:21], v[184:187], v[210:213], v[18:21]
	v_mfma_f32_16x16x32_bf16 v[6:9], v[176:179], v[218:221], v[6:9]
	v_mfma_f32_16x16x32_bf16 v[2:5], v[184:187], v[218:221], v[2:5]
	s_setprio 0
	s_add_i32 s80, s80, 2
	s_add_u32 s26, s26, 0x100
	s_addc_u32 s27, s27, 0
	s_add_u32 s58, s58, 0x100
	s_addc_u32 s59, s59, 0
	s_cmp_gt_u32 s80, 13
	s_barrier
	s_cbranch_scc0 .LBB0_374
	s_and_b64 vcc, exec, s[16:17]
	s_cbranch_vccz .LBB0_377
	s_barrier

.LBB0_1381:
	ds_read_b128 v[130:133], v215
	ds_read_b128 v[134:137], v215 offset:1024
	ds_read_b128 v[138:141], v215 offset:2048
	ds_read_b128 v[142:145], v215 offset:3072
	ds_read_b128 v[146:149], v216
	ds_read_b128 v[150:153], v216 offset:1024
	ds_read_b128 v[154:157], v216 offset:2048
	ds_read_b128 v[158:161], v216 offset:3072
	s_add_u32 s30, s28, 0xfffc0080
	s_addc_u32 s31, s29, -1
	s_cmp_eq_u32 s66, 12
	s_cselect_b32 s35, s21, s31
	s_cselect_b32 s34, s27, s30
	s_cselect_b32 s31, s19, s65
	s_cselect_b32 s30, s63, s64
	v_lshl_add_u64 v[224:225], s[28:29], 0, v[188:189]
	s_add_i32 m0, s40, 0xc000
	ds_read_b128 v[162:165], v217
	ds_read_b128 v[166:169], v217 offset:1024
	ds_read_b128 v[170:173], v217 offset:2048
	ds_read_b128 v[174:177], v217 offset:3072
	ds_read_b128 v[196:199], v217 offset:4096
	ds_read_b128 v[200:203], v217 offset:5120
	ds_read_b128 v[204:207], v217 offset:6144
	ds_read_b128 v[220:223], v217 offset:7168
	global_load_lds_dwordx4 v[224:225], off
	v_lshl_add_u64 v[224:225], s[28:29], 0, v[190:191]
	s_add_i32 m0, s40, 0xe000
	s_nop 0
	global_load_lds_dwordx4 v[224:225], off
	s_waitcnt vmcnt(8)
	s_waitcnt lgkmcnt(0)
	s_barrier
	s_setprio 1
	s_waitcnt lgkmcnt(0)
	v_mfma_f32_16x16x32_bf16 v[126:129], v[130:133], v[162:165], v[126:129]
	v_mfma_f32_16x16x32_bf16 v[122:125], v[138:141], v[162:165], v[122:125]
	v_mfma_f32_16x16x32_bf16 v[110:113], v[130:133], v[170:173], v[110:113]
	v_mfma_f32_16x16x32_bf16 v[106:109], v[138:141], v[170:173], v[106:109]
	v_mfma_f32_16x16x32_bf16 v[94:97], v[130:133], v[196:199], v[94:97]
	v_mfma_f32_16x16x32_bf16 v[90:93], v[138:141], v[196:199], v[90:93]
	v_mfma_f32_16x16x32_bf16 v[78:81], v[130:133], v[204:207], v[78:81]
	v_mfma_f32_16x16x32_bf16 v[74:77], v[138:141], v[204:207], v[74:77]
	v_mfma_f32_16x16x32_bf16 v[126:129], v[134:137], v[166:169], v[126:129]
	v_mfma_f32_16x16x32_bf16 v[122:125], v[142:145], v[166:169], v[122:125]
	v_mfma_f32_16x16x32_bf16 v[110:113], v[134:137], v[174:177], v[110:113]
	v_mfma_f32_16x16x32_bf16 v[106:109], v[142:145], v[174:177], v[106:109]
	v_mfma_f32_16x16x32_bf16 v[94:97], v[134:137], v[200:203], v[94:97]
	v_mfma_f32_16x16x32_bf16 v[90:93], v[142:145], v[200:203], v[90:93]
	v_mfma_f32_16x16x32_bf16 v[78:81], v[134:137], v[220:223], v[78:81]
	v_mfma_f32_16x16x32_bf16 v[74:77], v[142:145], v[220:223], v[74:77]
	s_setprio 0
	s_setprio 1
	v_mfma_f32_16x16x32_bf16 v[118:121], v[146:149], v[162:165], v[118:121]
	v_mfma_f32_16x16x32_bf16 v[114:117], v[154:157], v[162:165], v[114:117]
	v_mfma_f32_16x16x32_bf16 v[102:105], v[146:149], v[170:173], v[102:105]
	v_mfma_f32_16x16x32_bf16 v[98:101], v[154:157], v[170:173], v[98:101]
	v_mfma_f32_16x16x32_bf16 v[86:89], v[146:149], v[196:199], v[86:89]
	v_mfma_f32_16x16x32_bf16 v[82:85], v[154:157], v[196:199], v[82:85]
	v_mfma_f32_16x16x32_bf16 v[70:73], v[146:149], v[204:207], v[70:73]
	v_mfma_f32_16x16x32_bf16 v[66:69], v[154:157], v[204:207], v[66:69]
	v_mfma_f32_16x16x32_bf16 v[118:121], v[150:153], v[166:169], v[118:121]
	v_mfma_f32_16x16x32_bf16 v[114:117], v[158:161], v[166:169], v[114:117]
	v_mfma_f32_16x16x32_bf16 v[102:105], v[150:153], v[174:177], v[102:105]
	v_mfma_f32_16x16x32_bf16 v[98:101], v[158:161], v[174:177], v[98:101]
	v_mfma_f32_16x16x32_bf16 v[86:89], v[150:153], v[200:203], v[86:89]
	v_mfma_f32_16x16x32_bf16 v[82:85], v[158:161], v[200:203], v[82:85]
	v_mfma_f32_16x16x32_bf16 v[70:73], v[150:153], v[220:223], v[70:73]
	v_mfma_f32_16x16x32_bf16 v[66:69], v[158:161], v[220:223], v[66:69]
	s_setprio 0
	s_barrier
	s_add_i32 s67, s56, s39
	v_lshl_add_u64 v[224:225], s[30:31], 0, v[182:183]
	s_mov_b32 m0, s67
	ds_read_b128 v[162:165], v217 offset:16384
	ds_read_b128 v[166:169], v217 offset:17408
	ds_read_b128 v[170:173], v217 offset:18432
	ds_read_b128 v[174:177], v217 offset:19456
	ds_read_b128 v[196:199], v217 offset:20480
	ds_read_b128 v[200:203], v217 offset:21504
	ds_read_b128 v[204:207], v217 offset:22528
	ds_read_b128 v[220:223], v217 offset:23552
	global_load_lds_dwordx4 v[224:225], off
	s_add_i32 m0, s67, 0x2000
	s_add_u32 s68, s30, 0x40000
	v_lshl_add_u64 v[226:227], s[30:31], 0, v[186:187]
	s_addc_u32 s69, s31, 0
	s_add_i32 s67, s57, s39
	global_load_lds_dwordx4 v[226:227], off
	v_lshl_add_u64 v[228:229], s[68:69], 0, v[182:183]
	s_mov_b32 m0, s67
	v_lshl_add_u64 v[230:231], s[34:35], 0, v[184:185]
	global_load_lds_dwordx4 v[228:229], off
	v_lshl_add_u64 v[228:229], s[68:69], 0, v[186:187]
	s_add_i32 m0, s67, 0x2000
	s_nop 0
	global_load_lds_dwordx4 v[228:229], off
	v_lshl_add_u64 v[228:229], s[34:35], 0, v[180:181]
	s_mov_b32 m0, s40
	s_nop 0
	global_load_lds_dwordx4 v[228:229], off
	s_mov_b32 m0, s41
	s_nop 0
	global_load_lds_dwordx4 v[230:231], off
	s_waitcnt vmcnt(8)
	s_waitcnt lgkmcnt(0)
	s_barrier
	s_setprio 1
	s_waitcnt lgkmcnt(0)
	v_mfma_f32_16x16x32_bf16 v[62:65], v[130:133], v[162:165], v[62:65]
	v_mfma_f32_16x16x32_bf16 v[58:61], v[138:141], v[162:165], v[58:61]
	v_mfma_f32_16x16x32_bf16 v[46:49], v[130:133], v[170:173], v[46:49]
	v_mfma_f32_16x16x32_bf16 v[42:45], v[138:141], v[170:173], v[42:45]
	v_mfma_f32_16x16x32_bf16 v[30:33], v[130:133], v[196:199], v[30:33]
	v_mfma_f32_16x16x32_bf16 v[26:29], v[138:141], v[196:199], v[26:29]
	v_mfma_f32_16x16x32_bf16 v[14:17], v[130:133], v[204:207], v[14:17]
	v_mfma_f32_16x16x32_bf16 v[10:13], v[138:141], v[204:207], v[10:13]
	v_mfma_f32_16x16x32_bf16 v[62:65], v[134:137], v[166:169], v[62:65]
	v_mfma_f32_16x16x32_bf16 v[58:61], v[142:145], v[166:169], v[58:61]
	v_mfma_f32_16x16x32_bf16 v[46:49], v[134:137], v[174:177], v[46:49]
	v_mfma_f32_16x16x32_bf16 v[42:45], v[142:145], v[174:177], v[42:45]
	v_mfma_f32_16x16x32_bf16 v[30:33], v[134:137], v[200:203], v[30:33]
	v_mfma_f32_16x16x32_bf16 v[26:29], v[142:145], v[200:203], v[26:29]
	v_mfma_f32_16x16x32_bf16 v[14:17], v[134:137], v[220:223], v[14:17]
	v_mfma_f32_16x16x32_bf16 v[10:13], v[142:145], v[220:223], v[10:13]
	s_setprio 0
	s_setprio 1
	v_mfma_f32_16x16x32_bf16 v[54:57], v[146:149], v[162:165], v[54:57]
	v_mfma_f32_16x16x32_bf16 v[50:53], v[154:157], v[162:165], v[50:53]
	v_mfma_f32_16x16x32_bf16 v[38:41], v[146:149], v[170:173], v[38:41]
	v_mfma_f32_16x16x32_bf16 v[34:37], v[154:157], v[170:173], v[34:37]
	v_mfma_f32_16x16x32_bf16 v[22:25], v[146:149], v[196:199], v[22:25]
	v_mfma_f32_16x16x32_bf16 v[18:21], v[154:157], v[196:199], v[18:21]
	v_mfma_f32_16x16x32_bf16 v[6:9], v[146:149], v[204:207], v[6:9]
	v_mfma_f32_16x16x32_bf16 v[2:5], v[154:157], v[204:207], v[2:5]
	v_mfma_f32_16x16x32_bf16 v[54:57], v[150:153], v[166:169], v[54:57]
	v_mfma_f32_16x16x32_bf16 v[50:53], v[158:161], v[166:169], v[50:53]
	v_mfma_f32_16x16x32_bf16 v[38:41], v[150:153], v[174:177], v[38:41]
	v_mfma_f32_16x16x32_bf16 v[34:37], v[158:161], v[174:177], v[34:37]
	v_mfma_f32_16x16x32_bf16 v[22:25], v[150:153], v[200:203], v[22:25]
	v_mfma_f32_16x16x32_bf16 v[18:21], v[158:161], v[200:203], v[18:21]
	v_mfma_f32_16x16x32_bf16 v[6:9], v[150:153], v[220:223], v[6:9]
	v_mfma_f32_16x16x32_bf16 v[2:5], v[158:161], v[220:223], v[2:5]
	s_setprio 0
	s_barrier
	s_add_i32 s67, 0, 0x18000
	s_add_i32 s68, 0, 0x1c000
	v_add_u32_e32 v142, s67, v213
	v_add_u32_e32 v158, s68, v213
	ds_read_b128 v[130:133], v142
	ds_read_b128 v[134:137], v142 offset:1024
	ds_read_b128 v[138:141], v142 offset:2048
	ds_read_b128 v[142:145], v142 offset:3072
	ds_read_b128 v[146:149], v158
	ds_read_b128 v[150:153], v158 offset:1024
	ds_read_b128 v[154:157], v158 offset:2048
	ds_read_b128 v[158:161], v158 offset:3072
	s_add_u32 s34, s34, 0x40000
	s_addc_u32 s35, s35, 0
	s_mov_b32 m0, s42
	v_lshl_add_u64 v[232:233], s[34:35], 0, v[180:181]
	ds_read_b128 v[162:165], v217 offset:32768
	ds_read_b128 v[166:169], v217 offset:33792
	ds_read_b128 v[170:173], v217 offset:34816
	ds_read_b128 v[174:177], v217 offset:35840
	ds_read_b128 v[196:199], v217 offset:36864
	ds_read_b128 v[200:203], v217 offset:37888
	ds_read_b128 v[204:207], v217 offset:38912
	ds_read_b128 v[220:223], v217 offset:39936
	global_load_lds_dwordx4 v[232:233], off
	v_lshl_add_u64 v[232:233], s[34:35], 0, v[184:185]
	s_mov_b32 m0, s43
	s_nop 0
	global_load_lds_dwordx4 v[232:233], off
	s_waitcnt vmcnt(8)
	s_waitcnt lgkmcnt(0)
	s_barrier
	s_setprio 1
	s_waitcnt lgkmcnt(0)
	v_mfma_f32_16x16x32_bf16 v[126:129], v[130:133], v[162:165], v[126:129]
	v_mfma_f32_16x16x32_bf16 v[122:125], v[138:141], v[162:165], v[122:125]
	v_mfma_f32_16x16x32_bf16 v[110:113], v[130:133], v[170:173], v[110:113]
	v_mfma_f32_16x16x32_bf16 v[106:109], v[138:141], v[170:173], v[106:109]
	v_mfma_f32_16x16x32_bf16 v[94:97], v[130:133], v[196:199], v[94:97]
	v_mfma_f32_16x16x32_bf16 v[90:93], v[138:141], v[196:199], v[90:93]
	v_mfma_f32_16x16x32_bf16 v[78:81], v[130:133], v[204:207], v[78:81]
	v_mfma_f32_16x16x32_bf16 v[74:77], v[138:141], v[204:207], v[74:77]
	v_mfma_f32_16x16x32_bf16 v[126:129], v[134:137], v[166:169], v[126:129]
	v_mfma_f32_16x16x32_bf16 v[122:125], v[142:145], v[166:169], v[122:125]
	v_mfma_f32_16x16x32_bf16 v[110:113], v[134:137], v[174:177], v[110:113]
	v_mfma_f32_16x16x32_bf16 v[106:109], v[142:145], v[174:177], v[106:109]
	v_mfma_f32_16x16x32_bf16 v[94:97], v[134:137], v[200:203], v[94:97]
	v_mfma_f32_16x16x32_bf16 v[90:93], v[142:145], v[200:203], v[90:93]
	v_mfma_f32_16x16x32_bf16 v[78:81], v[134:137], v[220:223], v[78:81]
	v_mfma_f32_16x16x32_bf16 v[74:77], v[142:145], v[220:223], v[74:77]
	s_setprio 0
	s_setprio 1
	v_mfma_f32_16x16x32_bf16 v[118:121], v[146:149], v[162:165], v[118:121]
	v_mfma_f32_16x16x32_bf16 v[114:117], v[154:157], v[162:165], v[114:117]
	v_mfma_f32_16x16x32_bf16 v[102:105], v[146:149], v[170:173], v[102:105]
	v_mfma_f32_16x16x32_bf16 v[98:101], v[154:157], v[170:173], v[98:101]
	v_mfma_f32_16x16x32_bf16 v[86:89], v[146:149], v[196:199], v[86:89]
	v_mfma_f32_16x16x32_bf16 v[82:85], v[154:157], v[196:199], v[82:85]
	v_mfma_f32_16x16x32_bf16 v[70:73], v[146:149], v[204:207], v[70:73]
	v_mfma_f32_16x16x32_bf16 v[66:69], v[154:157], v[204:207], v[66:69]
	v_mfma_f32_16x16x32_bf16 v[118:121], v[150:153], v[166:169], v[118:121]
	v_mfma_f32_16x16x32_bf16 v[114:117], v[158:161], v[166:169], v[114:117]
	v_mfma_f32_16x16x32_bf16 v[102:105], v[150:153], v[174:177], v[102:105]
	v_mfma_f32_16x16x32_bf16 v[98:101], v[158:161], v[174:177], v[98:101]
	v_mfma_f32_16x16x32_bf16 v[86:89], v[150:153], v[200:203], v[86:89]
	v_mfma_f32_16x16x32_bf16 v[82:85], v[158:161], v[200:203], v[82:85]
	v_mfma_f32_16x16x32_bf16 v[70:73], v[150:153], v[220:223], v[70:73]
	v_mfma_f32_16x16x32_bf16 v[66:69], v[158:161], v[220:223], v[66:69]
	s_setprio 0
	s_barrier
	s_add_i32 s34, s67, s39
	v_lshl_add_u64 v[224:225], v[224:225], 0, s[14:15]
	s_mov_b32 m0, s34
	ds_read_b128 v[162:165], v217 offset:49152
	ds_read_b128 v[166:169], v217 offset:50176
	ds_read_b128 v[170:173], v217 offset:51200
	ds_read_b128 v[174:177], v217 offset:52224
	ds_read_b128 v[196:199], v217 offset:53248
	ds_read_b128 v[200:203], v217 offset:54272
	ds_read_b128 v[204:207], v217 offset:55296
	ds_read_b128 v[220:223], v217 offset:56320
	global_load_lds_dwordx4 v[224:225], off
	s_add_i32 m0, s34, 0x2000
	s_add_u32 s30, s30, 0x40080
	v_lshl_add_u64 v[224:225], v[226:227], 0, s[14:15]
	s_addc_u32 s31, s31, 0
	s_add_i32 s34, s68, s39
	global_load_lds_dwordx4 v[224:225], off
	v_lshl_add_u64 v[224:225], s[30:31], 0, v[182:183]
	s_mov_b32 m0, s34
	s_nop 0
	global_load_lds_dwordx4 v[224:225], off
	v_lshl_add_u64 v[224:225], s[30:31], 0, v[186:187]
	s_add_i32 m0, s34, 0x2000
	s_nop 0
	global_load_lds_dwordx4 v[224:225], off
	v_lshl_add_u64 v[224:225], v[228:229], 0, s[14:15]
	s_mov_b32 m0, s52
	s_nop 0
	global_load_lds_dwordx4 v[224:225], off
	v_lshl_add_u64 v[224:225], v[230:231], 0, s[14:15]
	s_mov_b32 m0, s53
	s_nop 0
	global_load_lds_dwordx4 v[224:225], off
	s_waitcnt vmcnt(8)
	s_waitcnt lgkmcnt(0)
	s_barrier
	s_setprio 1
	s_waitcnt lgkmcnt(0)
	v_mfma_f32_16x16x32_bf16 v[62:65], v[130:133], v[162:165], v[62:65]
	v_mfma_f32_16x16x32_bf16 v[58:61], v[138:141], v[162:165], v[58:61]
	v_mfma_f32_16x16x32_bf16 v[46:49], v[130:133], v[170:173], v[46:49]
	v_mfma_f32_16x16x32_bf16 v[42:45], v[138:141], v[170:173], v[42:45]
	v_mfma_f32_16x16x32_bf16 v[30:33], v[130:133], v[196:199], v[30:33]
	v_mfma_f32_16x16x32_bf16 v[26:29], v[138:141], v[196:199], v[26:29]
	v_mfma_f32_16x16x32_bf16 v[14:17], v[130:133], v[204:207], v[14:17]
	v_mfma_f32_16x16x32_bf16 v[10:13], v[138:141], v[204:207], v[10:13]
	v_mfma_f32_16x16x32_bf16 v[62:65], v[134:137], v[166:169], v[62:65]
	v_mfma_f32_16x16x32_bf16 v[58:61], v[142:145], v[166:169], v[58:61]
	v_mfma_f32_16x16x32_bf16 v[46:49], v[134:137], v[174:177], v[46:49]
	v_mfma_f32_16x16x32_bf16 v[42:45], v[142:145], v[174:177], v[42:45]
	v_mfma_f32_16x16x32_bf16 v[30:33], v[134:137], v[200:203], v[30:33]
	v_mfma_f32_16x16x32_bf16 v[26:29], v[142:145], v[200:203], v[26:29]
	v_mfma_f32_16x16x32_bf16 v[14:17], v[134:137], v[220:223], v[14:17]
	v_mfma_f32_16x16x32_bf16 v[10:13], v[142:145], v[220:223], v[10:13]
	s_setprio 0
	s_setprio 1
	v_mfma_f32_16x16x32_bf16 v[54:57], v[146:149], v[162:165], v[54:57]
	v_mfma_f32_16x16x32_bf16 v[50:53], v[154:157], v[162:165], v[50:53]
	v_mfma_f32_16x16x32_bf16 v[38:41], v[146:149], v[170:173], v[38:41]
	v_mfma_f32_16x16x32_bf16 v[34:37], v[154:157], v[170:173], v[34:37]
	v_mfma_f32_16x16x32_bf16 v[22:25], v[146:149], v[196:199], v[22:25]
	v_mfma_f32_16x16x32_bf16 v[18:21], v[154:157], v[196:199], v[18:21]
	v_mfma_f32_16x16x32_bf16 v[6:9], v[146:149], v[204:207], v[6:9]
	v_mfma_f32_16x16x32_bf16 v[2:5], v[154:157], v[204:207], v[2:5]
	v_mfma_f32_16x16x32_bf16 v[54:57], v[150:153], v[166:169], v[54:57]
	v_mfma_f32_16x16x32_bf16 v[50:53], v[158:161], v[166:169], v[50:53]
	v_mfma_f32_16x16x32_bf16 v[38:41], v[150:153], v[174:177], v[38:41]
	v_mfma_f32_16x16x32_bf16 v[34:37], v[158:161], v[174:177], v[34:37]
	v_mfma_f32_16x16x32_bf16 v[22:25], v[150:153], v[200:203], v[22:25]
	v_mfma_f32_16x16x32_bf16 v[18:21], v[158:161], v[200:203], v[18:21]
	v_mfma_f32_16x16x32_bf16 v[6:9], v[150:153], v[220:223], v[6:9]
	v_mfma_f32_16x16x32_bf16 v[2:5], v[158:161], v[220:223], v[2:5]
	s_setprio 0
	s_add_i32 s66, s66, 2
	s_add_u32 s28, s28, 0x100
	s_addc_u32 s29, s29, 0
	s_add_u32 s64, s64, 0x100
	s_addc_u32 s65, s65, 0
	s_cmp_gt_u32 s66, 13
	s_barrier
	s_cbranch_scc0 .LBB0_1381
	s_and_b64 vcc, exec, s[16:17]
	s_cbranch_vccz .LBB0_1384
	s_barrier

.Lp5_nozero:
.LBB0_1558:
	ds_read_b128 v[146:149], v153
	ds_read_b128 v[156:159], v153 offset:1024
	ds_read_b128 v[160:163], v153 offset:2048
	ds_read_b128 v[164:167], v153 offset:3072
	ds_read_b128 v[168:171], v154
	ds_read_b128 v[172:175], v154 offset:1024
	ds_read_b128 v[180:183], v154 offset:2048
	ds_read_b128 v[184:187], v154 offset:3072
	s_add_u32 s26, s24, 0xfffc0080
	s_addc_u32 s27, s25, -1
	s_cmp_eq_u32 s55, 12
	s_cselect_b32 s29, s17, s27
	s_cselect_b32 s28, s51, s26
	s_cselect_b32 s27, s15, s54
	s_cselect_b32 s26, s52, s53
	v_lshl_add_u64 v[176:177], s[24:25], 0, v[138:139]
	s_add_i32 m0, s23, 0xc000
	ds_read_b128 v[188:191], v155
	ds_read_b128 v[192:195], v155 offset:1024
	ds_read_b128 v[196:199], v155 offset:2048
	ds_read_b128 v[200:203], v155 offset:3072
	ds_read_b128 v[204:207], v155 offset:4096
	ds_read_b128 v[210:213], v155 offset:5120
	ds_read_b128 v[214:217], v155 offset:6144
	ds_read_b128 v[218:221], v155 offset:7168
	global_load_lds_dwordx4 v[176:177], off
	v_lshl_add_u64 v[176:177], s[24:25], 0, v[140:141]
	s_add_i32 m0, s23, 0xe000
	s_nop 0
	global_load_lds_dwordx4 v[176:177], off
	s_waitcnt vmcnt(8)
	s_waitcnt lgkmcnt(0)
	s_barrier
	s_setprio 1
	s_waitcnt lgkmcnt(0)
	v_mfma_f32_16x16x32_bf16 v[122:125], v[146:149], v[188:191], v[122:125]
	v_mfma_f32_16x16x32_bf16 v[114:117], v[160:163], v[188:191], v[114:117]
	v_mfma_f32_16x16x32_bf16 v[106:109], v[146:149], v[196:199], v[106:109]
	v_mfma_f32_16x16x32_bf16 v[98:101], v[160:163], v[196:199], v[98:101]
	v_mfma_f32_16x16x32_bf16 v[90:93], v[146:149], v[204:207], v[90:93]
	v_mfma_f32_16x16x32_bf16 v[82:85], v[160:163], v[204:207], v[82:85]
	v_mfma_f32_16x16x32_bf16 v[74:77], v[146:149], v[214:217], v[74:77]
	v_mfma_f32_16x16x32_bf16 v[70:73], v[160:163], v[214:217], v[70:73]
	v_mfma_f32_16x16x32_bf16 v[122:125], v[156:159], v[192:195], v[122:125]
	v_mfma_f32_16x16x32_bf16 v[114:117], v[164:167], v[192:195], v[114:117]
	v_mfma_f32_16x16x32_bf16 v[106:109], v[156:159], v[200:203], v[106:109]
	v_mfma_f32_16x16x32_bf16 v[98:101], v[164:167], v[200:203], v[98:101]
	v_mfma_f32_16x16x32_bf16 v[90:93], v[156:159], v[210:213], v[90:93]
	v_mfma_f32_16x16x32_bf16 v[82:85], v[164:167], v[210:213], v[82:85]
	v_mfma_f32_16x16x32_bf16 v[74:77], v[156:159], v[218:221], v[74:77]
	v_mfma_f32_16x16x32_bf16 v[70:73], v[164:167], v[218:221], v[70:73]
	s_setprio 0
	s_setprio 1
	v_mfma_f32_16x16x32_bf16 v[126:129], v[168:171], v[188:191], v[126:129]
	v_mfma_f32_16x16x32_bf16 v[118:121], v[180:183], v[188:191], v[118:121]
	v_mfma_f32_16x16x32_bf16 v[110:113], v[168:171], v[196:199], v[110:113]
	v_mfma_f32_16x16x32_bf16 v[102:105], v[180:183], v[196:199], v[102:105]
	v_mfma_f32_16x16x32_bf16 v[94:97], v[168:171], v[204:207], v[94:97]
	v_mfma_f32_16x16x32_bf16 v[86:89], v[180:183], v[204:207], v[86:89]
	v_mfma_f32_16x16x32_bf16 v[78:81], v[168:171], v[214:217], v[78:81]
	v_mfma_f32_16x16x32_bf16 v[66:69], v[180:183], v[214:217], v[66:69]
	v_mfma_f32_16x16x32_bf16 v[126:129], v[172:175], v[192:195], v[126:129]
	v_mfma_f32_16x16x32_bf16 v[118:121], v[184:187], v[192:195], v[118:121]
	v_mfma_f32_16x16x32_bf16 v[110:113], v[172:175], v[200:203], v[110:113]
	v_mfma_f32_16x16x32_bf16 v[102:105], v[184:187], v[200:203], v[102:105]
	v_mfma_f32_16x16x32_bf16 v[94:97], v[172:175], v[210:213], v[94:97]
	v_mfma_f32_16x16x32_bf16 v[86:89], v[184:187], v[210:213], v[86:89]
	v_mfma_f32_16x16x32_bf16 v[78:81], v[172:175], v[218:221], v[78:81]
	v_mfma_f32_16x16x32_bf16 v[66:69], v[184:187], v[218:221], v[66:69]
	s_setprio 0
	s_barrier
	s_add_i32 s56, s45, s35
	v_lshl_add_u64 v[176:177], s[26:27], 0, v[134:135]
	s_mov_b32 m0, s56
	ds_read_b128 v[188:191], v155 offset:16384
	ds_read_b128 v[192:195], v155 offset:17408
	ds_read_b128 v[196:199], v155 offset:18432
	ds_read_b128 v[200:203], v155 offset:19456
	ds_read_b128 v[204:207], v155 offset:20480
	ds_read_b128 v[210:213], v155 offset:21504
	ds_read_b128 v[214:217], v155 offset:22528
	ds_read_b128 v[218:221], v155 offset:23552
	global_load_lds_dwordx4 v[176:177], off
	s_add_i32 m0, s56, 0x2000
	s_add_u32 s56, s26, 0x40000
	v_lshl_add_u64 v[208:209], s[26:27], 0, v[130:131]
	s_addc_u32 s57, s27, 0
	s_add_i32 s58, s48, s35
	global_load_lds_dwordx4 v[208:209], off
	v_lshl_add_u64 v[222:223], s[56:57], 0, v[134:135]
	s_mov_b32 m0, s58
	v_lshl_add_u64 v[224:225], s[28:29], 0, v[132:133]
	global_load_lds_dwordx4 v[222:223], off
	v_lshl_add_u64 v[222:223], s[56:57], 0, v[130:131]
	s_add_i32 m0, s58, 0x2000
	s_nop 0
	global_load_lds_dwordx4 v[222:223], off
	v_lshl_add_u64 v[222:223], s[28:29], 0, v[136:137]
	s_mov_b32 m0, s23
	s_nop 0
	global_load_lds_dwordx4 v[222:223], off
	s_mov_b32 m0, s38
	s_nop 0
	global_load_lds_dwordx4 v[224:225], off
	s_waitcnt vmcnt(8)
	s_waitcnt lgkmcnt(0)
	s_barrier
	s_setprio 1
	s_waitcnt lgkmcnt(0)
	v_mfma_f32_16x16x32_bf16 v[58:61], v[146:149], v[188:191], v[58:61]
	v_mfma_f32_16x16x32_bf16 v[54:57], v[160:163], v[188:191], v[54:57]
	v_mfma_f32_16x16x32_bf16 v[42:45], v[146:149], v[196:199], v[42:45]
	v_mfma_f32_16x16x32_bf16 v[38:41], v[160:163], v[196:199], v[38:41]
	v_mfma_f32_16x16x32_bf16 v[26:29], v[146:149], v[204:207], v[26:29]
	v_mfma_f32_16x16x32_bf16 v[22:25], v[160:163], v[204:207], v[22:25]
	v_mfma_f32_16x16x32_bf16 v[10:13], v[146:149], v[214:217], v[10:13]
	v_mfma_f32_16x16x32_bf16 v[6:9], v[160:163], v[214:217], v[6:9]
	v_mfma_f32_16x16x32_bf16 v[58:61], v[156:159], v[192:195], v[58:61]
	v_mfma_f32_16x16x32_bf16 v[54:57], v[164:167], v[192:195], v[54:57]
	v_mfma_f32_16x16x32_bf16 v[42:45], v[156:159], v[200:203], v[42:45]
	v_mfma_f32_16x16x32_bf16 v[38:41], v[164:167], v[200:203], v[38:41]
	v_mfma_f32_16x16x32_bf16 v[26:29], v[156:159], v[210:213], v[26:29]
	v_mfma_f32_16x16x32_bf16 v[22:25], v[164:167], v[210:213], v[22:25]
	v_mfma_f32_16x16x32_bf16 v[10:13], v[156:159], v[218:221], v[10:13]
	v_mfma_f32_16x16x32_bf16 v[6:9], v[164:167], v[218:221], v[6:9]
	s_setprio 0
	s_setprio 1
	v_mfma_f32_16x16x32_bf16 v[62:65], v[168:171], v[188:191], v[62:65]
	v_mfma_f32_16x16x32_bf16 v[50:53], v[180:183], v[188:191], v[50:53]
	v_mfma_f32_16x16x32_bf16 v[46:49], v[168:171], v[196:199], v[46:49]
	v_mfma_f32_16x16x32_bf16 v[34:37], v[180:183], v[196:199], v[34:37]
	v_mfma_f32_16x16x32_bf16 v[30:33], v[168:171], v[204:207], v[30:33]
	v_mfma_f32_16x16x32_bf16 v[18:21], v[180:183], v[204:207], v[18:21]
	v_mfma_f32_16x16x32_bf16 v[14:17], v[168:171], v[214:217], v[14:17]
	v_mfma_f32_16x16x32_bf16 v[2:5], v[180:183], v[214:217], v[2:5]
	v_mfma_f32_16x16x32_bf16 v[62:65], v[172:175], v[192:195], v[62:65]
	v_mfma_f32_16x16x32_bf16 v[50:53], v[184:187], v[192:195], v[50:53]
	v_mfma_f32_16x16x32_bf16 v[46:49], v[172:175], v[200:203], v[46:49]
	v_mfma_f32_16x16x32_bf16 v[34:37], v[184:187], v[200:203], v[34:37]
	v_mfma_f32_16x16x32_bf16 v[30:33], v[172:175], v[210:213], v[30:33]
	v_mfma_f32_16x16x32_bf16 v[18:21], v[184:187], v[210:213], v[18:21]
	v_mfma_f32_16x16x32_bf16 v[14:17], v[172:175], v[218:221], v[14:17]
	v_mfma_f32_16x16x32_bf16 v[2:5], v[184:187], v[218:221], v[2:5]
	s_setprio 0
	s_barrier
	s_add_i32 s56, 0, 0x18000
	s_add_i32 s57, 0, 0x1c000
	v_add_u32_e32 v164, s56, v151
	v_add_u32_e32 v179, s57, v151
	ds_read_b128 v[146:149], v164
	ds_read_b128 v[156:159], v164 offset:1024
	ds_read_b128 v[160:163], v164 offset:2048
	ds_read_b128 v[164:167], v164 offset:3072
	ds_read_b128 v[168:171], v179
	ds_read_b128 v[172:175], v179 offset:1024
	ds_read_b128 v[180:183], v179 offset:2048
	ds_read_b128 v[184:187], v179 offset:3072
	s_add_u32 s28, s28, 0x40000
	s_addc_u32 s29, s29, 0
	s_mov_b32 m0, s39
	v_lshl_add_u64 v[226:227], s[28:29], 0, v[136:137]
	ds_read_b128 v[188:191], v155 offset:32768
	ds_read_b128 v[192:195], v155 offset:33792
	ds_read_b128 v[196:199], v155 offset:34816
	ds_read_b128 v[200:203], v155 offset:35840
	ds_read_b128 v[204:207], v155 offset:36864
	ds_read_b128 v[210:213], v155 offset:37888
	ds_read_b128 v[214:217], v155 offset:38912
	ds_read_b128 v[218:221], v155 offset:39936
	global_load_lds_dwordx4 v[226:227], off
	v_lshl_add_u64 v[226:227], s[28:29], 0, v[132:133]
	s_mov_b32 m0, s40
	s_nop 0
	global_load_lds_dwordx4 v[226:227], off
	s_waitcnt vmcnt(8)
	s_waitcnt lgkmcnt(0)
	s_barrier
	s_setprio 1
	s_waitcnt lgkmcnt(0)
	v_mfma_f32_16x16x32_bf16 v[122:125], v[146:149], v[188:191], v[122:125]
	v_mfma_f32_16x16x32_bf16 v[114:117], v[160:163], v[188:191], v[114:117]
	v_mfma_f32_16x16x32_bf16 v[106:109], v[146:149], v[196:199], v[106:109]
	v_mfma_f32_16x16x32_bf16 v[98:101], v[160:163], v[196:199], v[98:101]
	v_mfma_f32_16x16x32_bf16 v[90:93], v[146:149], v[204:207], v[90:93]
	v_mfma_f32_16x16x32_bf16 v[82:85], v[160:163], v[204:207], v[82:85]
	v_mfma_f32_16x16x32_bf16 v[74:77], v[146:149], v[214:217], v[74:77]
	v_mfma_f32_16x16x32_bf16 v[70:73], v[160:163], v[214:217], v[70:73]
	v_mfma_f32_16x16x32_bf16 v[122:125], v[156:159], v[192:195], v[122:125]
	v_mfma_f32_16x16x32_bf16 v[114:117], v[164:167], v[192:195], v[114:117]
	v_mfma_f32_16x16x32_bf16 v[106:109], v[156:159], v[200:203], v[106:109]
	v_mfma_f32_16x16x32_bf16 v[98:101], v[164:167], v[200:203], v[98:101]
	v_mfma_f32_16x16x32_bf16 v[90:93], v[156:159], v[210:213], v[90:93]
	v_mfma_f32_16x16x32_bf16 v[82:85], v[164:167], v[210:213], v[82:85]
	v_mfma_f32_16x16x32_bf16 v[74:77], v[156:159], v[218:221], v[74:77]
	v_mfma_f32_16x16x32_bf16 v[70:73], v[164:167], v[218:221], v[70:73]
	s_setprio 0
	s_setprio 1
	v_mfma_f32_16x16x32_bf16 v[126:129], v[168:171], v[188:191], v[126:129]
	v_mfma_f32_16x16x32_bf16 v[118:121], v[180:183], v[188:191], v[118:121]
	v_mfma_f32_16x16x32_bf16 v[110:113], v[168:171], v[196:199], v[110:113]
	v_mfma_f32_16x16x32_bf16 v[102:105], v[180:183], v[196:199], v[102:105]
	v_mfma_f32_16x16x32_bf16 v[94:97], v[168:171], v[204:207], v[94:97]
	v_mfma_f32_16x16x32_bf16 v[86:89], v[180:183], v[204:207], v[86:89]
	v_mfma_f32_16x16x32_bf16 v[78:81], v[168:171], v[214:217], v[78:81]
	v_mfma_f32_16x16x32_bf16 v[66:69], v[180:183], v[214:217], v[66:69]
	v_mfma_f32_16x16x32_bf16 v[126:129], v[172:175], v[192:195], v[126:129]
	v_mfma_f32_16x16x32_bf16 v[118:121], v[184:187], v[192:195], v[118:121]
	v_mfma_f32_16x16x32_bf16 v[110:113], v[172:175], v[200:203], v[110:113]
	v_mfma_f32_16x16x32_bf16 v[102:105], v[184:187], v[200:203], v[102:105]
	v_mfma_f32_16x16x32_bf16 v[94:97], v[172:175], v[210:213], v[94:97]
	v_mfma_f32_16x16x32_bf16 v[86:89], v[184:187], v[210:213], v[86:89]
	v_mfma_f32_16x16x32_bf16 v[78:81], v[172:175], v[218:221], v[78:81]
	v_mfma_f32_16x16x32_bf16 v[66:69], v[184:187], v[218:221], v[66:69]
	s_setprio 0
	s_barrier
	s_add_i32 s28, s56, s35
	v_lshl_add_u64 v[176:177], v[176:177], 0, s[10:11]
	s_mov_b32 m0, s28
	ds_read_b128 v[188:191], v155 offset:49152
	ds_read_b128 v[192:195], v155 offset:50176
	ds_read_b128 v[196:199], v155 offset:51200
	ds_read_b128 v[200:203], v155 offset:52224
	ds_read_b128 v[204:207], v155 offset:53248
	ds_read_b128 v[210:213], v155 offset:54272
	ds_read_b128 v[214:217], v155 offset:55296
	ds_read_b128 v[218:221], v155 offset:56320
	global_load_lds_dwordx4 v[176:177], off
	s_add_i32 m0, s28, 0x2000
	s_add_u32 s26, s26, 0x40080
	v_lshl_add_u64 v[176:177], v[208:209], 0, s[10:11]
	s_addc_u32 s27, s27, 0
	s_add_i32 s28, s57, s35
	global_load_lds_dwordx4 v[176:177], off
	v_lshl_add_u64 v[176:177], s[26:27], 0, v[134:135]
	s_mov_b32 m0, s28
	s_nop 0
	global_load_lds_dwordx4 v[176:177], off
	v_lshl_add_u64 v[176:177], s[26:27], 0, v[130:131]
	s_add_i32 m0, s28, 0x2000
	s_nop 0
	global_load_lds_dwordx4 v[176:177], off
	v_lshl_add_u64 v[176:177], v[222:223], 0, s[10:11]
	s_mov_b32 m0, s42
	s_nop 0
	global_load_lds_dwordx4 v[176:177], off
	v_lshl_add_u64 v[176:177], v[224:225], 0, s[10:11]
	s_mov_b32 m0, s43
	s_nop 0
	global_load_lds_dwordx4 v[176:177], off
	s_waitcnt vmcnt(8)
	s_waitcnt lgkmcnt(0)
	s_barrier
	s_setprio 1
	s_waitcnt lgkmcnt(0)
	v_mfma_f32_16x16x32_bf16 v[58:61], v[146:149], v[188:191], v[58:61]
	v_mfma_f32_16x16x32_bf16 v[54:57], v[160:163], v[188:191], v[54:57]
	v_mfma_f32_16x16x32_bf16 v[42:45], v[146:149], v[196:199], v[42:45]
	v_mfma_f32_16x16x32_bf16 v[38:41], v[160:163], v[196:199], v[38:41]
	v_mfma_f32_16x16x32_bf16 v[26:29], v[146:149], v[204:207], v[26:29]
	v_mfma_f32_16x16x32_bf16 v[22:25], v[160:163], v[204:207], v[22:25]
	v_mfma_f32_16x16x32_bf16 v[10:13], v[146:149], v[214:217], v[10:13]
	v_mfma_f32_16x16x32_bf16 v[6:9], v[160:163], v[214:217], v[6:9]
	v_mfma_f32_16x16x32_bf16 v[58:61], v[156:159], v[192:195], v[58:61]
	v_mfma_f32_16x16x32_bf16 v[54:57], v[164:167], v[192:195], v[54:57]
	v_mfma_f32_16x16x32_bf16 v[42:45], v[156:159], v[200:203], v[42:45]
	v_mfma_f32_16x16x32_bf16 v[38:41], v[164:167], v[200:203], v[38:41]
	v_mfma_f32_16x16x32_bf16 v[26:29], v[156:159], v[210:213], v[26:29]
	v_mfma_f32_16x16x32_bf16 v[22:25], v[164:167], v[210:213], v[22:25]
	v_mfma_f32_16x16x32_bf16 v[10:13], v[156:159], v[218:221], v[10:13]
	v_mfma_f32_16x16x32_bf16 v[6:9], v[164:167], v[218:221], v[6:9]
	s_setprio 0
	s_setprio 1
	v_mfma_f32_16x16x32_bf16 v[62:65], v[168:171], v[188:191], v[62:65]
	v_mfma_f32_16x16x32_bf16 v[50:53], v[180:183], v[188:191], v[50:53]
	v_mfma_f32_16x16x32_bf16 v[46:49], v[168:171], v[196:199], v[46:49]
	v_mfma_f32_16x16x32_bf16 v[34:37], v[180:183], v[196:199], v[34:37]
	v_mfma_f32_16x16x32_bf16 v[30:33], v[168:171], v[204:207], v[30:33]
	v_mfma_f32_16x16x32_bf16 v[18:21], v[180:183], v[204:207], v[18:21]
	v_mfma_f32_16x16x32_bf16 v[14:17], v[168:171], v[214:217], v[14:17]
	v_mfma_f32_16x16x32_bf16 v[2:5], v[180:183], v[214:217], v[2:5]
	v_mfma_f32_16x16x32_bf16 v[62:65], v[172:175], v[192:195], v[62:65]
	v_mfma_f32_16x16x32_bf16 v[50:53], v[184:187], v[192:195], v[50:53]
	v_mfma_f32_16x16x32_bf16 v[46:49], v[172:175], v[200:203], v[46:49]
	v_mfma_f32_16x16x32_bf16 v[34:37], v[184:187], v[200:203], v[34:37]
	v_mfma_f32_16x16x32_bf16 v[30:33], v[172:175], v[210:213], v[30:33]
	v_mfma_f32_16x16x32_bf16 v[18:21], v[184:187], v[210:213], v[18:21]
	v_mfma_f32_16x16x32_bf16 v[14:17], v[172:175], v[218:221], v[14:17]
	v_mfma_f32_16x16x32_bf16 v[2:5], v[184:187], v[218:221], v[2:5]
	s_setprio 0
	s_add_i32 s55, s55, 2
	s_add_u32 s24, s24, 0x100
	s_addc_u32 s25, s25, 0
	s_add_u32 s53, s53, 0x100
	s_addc_u32 s54, s54, 0
	s_cmp_gt_u32 s55, 13
	s_barrier
	s_cbranch_scc0 .LBB0_1558
	s_and_b64 vcc, exec, s[12:13]
	s_cbranch_vccz .LBB0_1561
	s_barrier

.LBB0_1652:
	ds_read_b128 v[150:153], v161
	ds_read_b128 v[164:167], v161 offset:1024
	ds_read_b128 v[168:171], v161 offset:2048
	ds_read_b128 v[172:175], v161 offset:3072
	ds_read_b128 v[180:183], v162
	ds_read_b128 v[184:187], v162 offset:1024
	ds_read_b128 v[196:199], v162 offset:2048
	ds_read_b128 v[200:203], v162 offset:3072
	s_add_u32 s18, s16, 0xfff50080
	s_addc_u32 s19, s17, -1
	s_cmp_eq_u32 s41, 40
	s_cselect_b32 s21, s5, s19
	s_cselect_b32 s20, s4, s18
	s_cselect_b32 s19, s15, s40
	s_cselect_b32 s18, s14, s39
	v_lshl_add_u64 v[154:155], s[16:17], 0, v[142:143]
	s_add_i32 m0, s24, 0xc000
	ds_read_b128 v[204:207], v163
	ds_read_b128 v[210:213], v163 offset:1024
	ds_read_b128 v[214:217], v163 offset:2048
	ds_read_b128 v[218:221], v163 offset:3072
	ds_read_b128 v[222:225], v163 offset:4096
	ds_read_b128 v[226:229], v163 offset:5120
	ds_read_b128 v[230:233], v163 offset:6144
	ds_read_b128 v[234:237], v163 offset:7168
	global_load_lds_dwordx4 v[154:155], off
	v_lshl_add_u64 v[154:155], s[16:17], 0, v[144:145]
	s_add_i32 m0, s24, 0xe000
	s_nop 0
	global_load_lds_dwordx4 v[154:155], off
	s_waitcnt vmcnt(8)
	s_waitcnt lgkmcnt(0)
	s_barrier
	s_setprio 1
	s_waitcnt lgkmcnt(0)
	v_mfma_f32_16x16x32_bf16 v[126:129], v[150:153], v[204:207], v[126:129]
	v_mfma_f32_16x16x32_bf16 v[122:125], v[168:171], v[204:207], v[122:125]
	v_mfma_f32_16x16x32_bf16 v[110:113], v[150:153], v[214:217], v[110:113]
	v_mfma_f32_16x16x32_bf16 v[106:109], v[168:171], v[214:217], v[106:109]
	v_mfma_f32_16x16x32_bf16 v[94:97], v[150:153], v[222:225], v[94:97]
	v_mfma_f32_16x16x32_bf16 v[90:93], v[168:171], v[222:225], v[90:93]
	v_mfma_f32_16x16x32_bf16 v[78:81], v[150:153], v[230:233], v[78:81]
	v_mfma_f32_16x16x32_bf16 v[74:77], v[168:171], v[230:233], v[74:77]
	v_mfma_f32_16x16x32_bf16 v[126:129], v[164:167], v[210:213], v[126:129]
	v_mfma_f32_16x16x32_bf16 v[122:125], v[172:175], v[210:213], v[122:125]
	v_mfma_f32_16x16x32_bf16 v[110:113], v[164:167], v[218:221], v[110:113]
	v_mfma_f32_16x16x32_bf16 v[106:109], v[172:175], v[218:221], v[106:109]
	v_mfma_f32_16x16x32_bf16 v[94:97], v[164:167], v[226:229], v[94:97]
	v_mfma_f32_16x16x32_bf16 v[90:93], v[172:175], v[226:229], v[90:93]
	v_mfma_f32_16x16x32_bf16 v[78:81], v[164:167], v[234:237], v[78:81]
	v_mfma_f32_16x16x32_bf16 v[74:77], v[172:175], v[234:237], v[74:77]
	s_setprio 0
	s_setprio 1
	v_mfma_f32_16x16x32_bf16 v[118:121], v[180:183], v[204:207], v[118:121]
	v_mfma_f32_16x16x32_bf16 v[114:117], v[196:199], v[204:207], v[114:117]
	v_mfma_f32_16x16x32_bf16 v[102:105], v[180:183], v[214:217], v[102:105]
	v_mfma_f32_16x16x32_bf16 v[98:101], v[196:199], v[214:217], v[98:101]
	v_mfma_f32_16x16x32_bf16 v[86:89], v[180:183], v[222:225], v[86:89]
	v_mfma_f32_16x16x32_bf16 v[82:85], v[196:199], v[222:225], v[82:85]
	v_mfma_f32_16x16x32_bf16 v[70:73], v[180:183], v[230:233], v[70:73]
	v_mfma_f32_16x16x32_bf16 v[66:69], v[196:199], v[230:233], v[66:69]
	v_mfma_f32_16x16x32_bf16 v[118:121], v[184:187], v[210:213], v[118:121]
	v_mfma_f32_16x16x32_bf16 v[114:117], v[200:203], v[210:213], v[114:117]
	v_mfma_f32_16x16x32_bf16 v[102:105], v[184:187], v[218:221], v[102:105]
	v_mfma_f32_16x16x32_bf16 v[98:101], v[200:203], v[218:221], v[98:101]
	v_mfma_f32_16x16x32_bf16 v[86:89], v[184:187], v[226:229], v[86:89]
	v_mfma_f32_16x16x32_bf16 v[82:85], v[200:203], v[226:229], v[82:85]
	v_mfma_f32_16x16x32_bf16 v[70:73], v[184:187], v[234:237], v[70:73]
	v_mfma_f32_16x16x32_bf16 v[66:69], v[200:203], v[234:237], v[66:69]
	s_setprio 0
	s_barrier
	s_add_i32 s42, s33, s23
	v_lshl_add_u64 v[154:155], s[18:19], 0, v[132:133]
	s_mov_b32 m0, s42
	ds_read_b128 v[204:207], v163 offset:16384
	ds_read_b128 v[210:213], v163 offset:17408
	ds_read_b128 v[214:217], v163 offset:18432
	ds_read_b128 v[218:221], v163 offset:19456
	ds_read_b128 v[222:225], v163 offset:20480
	ds_read_b128 v[226:229], v163 offset:21504
	ds_read_b128 v[230:233], v163 offset:22528
	ds_read_b128 v[234:237], v163 offset:23552
	global_load_lds_dwordx4 v[154:155], off
	s_add_i32 m0, s42, 0x2000
	s_add_u32 s42, s18, 0xb0000
	v_lshl_add_u64 v[176:177], s[18:19], 0, v[136:137]
	s_addc_u32 s43, s19, 0
	s_add_i32 s44, s34, s23
	global_load_lds_dwordx4 v[176:177], off
	v_lshl_add_u64 v[188:189], s[42:43], 0, v[132:133]
	s_mov_b32 m0, s44
	v_lshl_add_u64 v[208:209], s[20:21], 0, v[134:135]
	global_load_lds_dwordx4 v[188:189], off
	v_lshl_add_u64 v[188:189], s[42:43], 0, v[136:137]
	s_add_i32 m0, s44, 0x2000
	s_nop 0
	global_load_lds_dwordx4 v[188:189], off
	v_lshl_add_u64 v[188:189], s[20:21], 0, v[130:131]
	s_mov_b32 m0, s24
	s_nop 0
	global_load_lds_dwordx4 v[188:189], off
	s_mov_b32 m0, s25
	s_nop 0
	global_load_lds_dwordx4 v[208:209], off
	s_waitcnt vmcnt(8)
	s_waitcnt lgkmcnt(0)
	s_barrier
	s_setprio 1
	s_waitcnt lgkmcnt(0)
	v_mfma_f32_16x16x32_bf16 v[62:65], v[150:153], v[204:207], v[62:65]
	v_mfma_f32_16x16x32_bf16 v[58:61], v[168:171], v[204:207], v[58:61]
	v_mfma_f32_16x16x32_bf16 v[46:49], v[150:153], v[214:217], v[46:49]
	v_mfma_f32_16x16x32_bf16 v[42:45], v[168:171], v[214:217], v[42:45]
	v_mfma_f32_16x16x32_bf16 v[30:33], v[150:153], v[222:225], v[30:33]
	v_mfma_f32_16x16x32_bf16 v[26:29], v[168:171], v[222:225], v[26:29]
	v_mfma_f32_16x16x32_bf16 v[14:17], v[150:153], v[230:233], v[14:17]
	v_mfma_f32_16x16x32_bf16 v[10:13], v[168:171], v[230:233], v[10:13]
	v_mfma_f32_16x16x32_bf16 v[62:65], v[164:167], v[210:213], v[62:65]
	v_mfma_f32_16x16x32_bf16 v[58:61], v[172:175], v[210:213], v[58:61]
	v_mfma_f32_16x16x32_bf16 v[46:49], v[164:167], v[218:221], v[46:49]
	v_mfma_f32_16x16x32_bf16 v[42:45], v[172:175], v[218:221], v[42:45]
	v_mfma_f32_16x16x32_bf16 v[30:33], v[164:167], v[226:229], v[30:33]
	v_mfma_f32_16x16x32_bf16 v[26:29], v[172:175], v[226:229], v[26:29]
	v_mfma_f32_16x16x32_bf16 v[14:17], v[164:167], v[234:237], v[14:17]
	v_mfma_f32_16x16x32_bf16 v[10:13], v[172:175], v[234:237], v[10:13]
	s_setprio 0
	s_setprio 1
	v_mfma_f32_16x16x32_bf16 v[54:57], v[180:183], v[204:207], v[54:57]
	v_mfma_f32_16x16x32_bf16 v[50:53], v[196:199], v[204:207], v[50:53]
	v_mfma_f32_16x16x32_bf16 v[38:41], v[180:183], v[214:217], v[38:41]
	v_mfma_f32_16x16x32_bf16 v[34:37], v[196:199], v[214:217], v[34:37]
	v_mfma_f32_16x16x32_bf16 v[22:25], v[180:183], v[222:225], v[22:25]
	v_mfma_f32_16x16x32_bf16 v[18:21], v[196:199], v[222:225], v[18:21]
	v_mfma_f32_16x16x32_bf16 v[6:9], v[180:183], v[230:233], v[6:9]
	v_mfma_f32_16x16x32_bf16 v[2:5], v[196:199], v[230:233], v[2:5]
	v_mfma_f32_16x16x32_bf16 v[54:57], v[184:187], v[210:213], v[54:57]
	v_mfma_f32_16x16x32_bf16 v[50:53], v[200:203], v[210:213], v[50:53]
	v_mfma_f32_16x16x32_bf16 v[38:41], v[184:187], v[218:221], v[38:41]
	v_mfma_f32_16x16x32_bf16 v[34:37], v[200:203], v[218:221], v[34:37]
	v_mfma_f32_16x16x32_bf16 v[22:25], v[184:187], v[226:229], v[22:25]
	v_mfma_f32_16x16x32_bf16 v[18:21], v[200:203], v[226:229], v[18:21]
	v_mfma_f32_16x16x32_bf16 v[6:9], v[184:187], v[234:237], v[6:9]
	v_mfma_f32_16x16x32_bf16 v[2:5], v[200:203], v[234:237], v[2:5]
	s_setprio 0
	s_barrier
	s_add_i32 s42, 0, 0x18000
	v_add_u32_e32 v139, s42, v159
	s_add_i32 s43, 0, 0x1c000
	ds_read_b128 v[150:153], v139
	ds_read_b128 v[164:167], v139 offset:1024
	ds_read_b128 v[168:171], v139 offset:2048
	ds_read_b128 v[172:175], v139 offset:3072
	v_add_u32_e32 v139, s43, v159
	ds_read_b128 v[180:183], v139
	ds_read_b128 v[184:187], v139 offset:1024
	ds_read_b128 v[196:199], v139 offset:2048
	ds_read_b128 v[200:203], v139 offset:3072
	s_add_u32 s20, s20, 0xb0000
	s_addc_u32 s21, s21, 0
	s_mov_b32 m0, s26
	v_lshl_add_u64 v[238:239], s[20:21], 0, v[130:131]
	ds_read_b128 v[204:207], v163 offset:32768
	ds_read_b128 v[210:213], v163 offset:33792
	ds_read_b128 v[214:217], v163 offset:34816
	ds_read_b128 v[218:221], v163 offset:35840
	ds_read_b128 v[222:225], v163 offset:36864
	ds_read_b128 v[226:229], v163 offset:37888
	ds_read_b128 v[230:233], v163 offset:38912
	ds_read_b128 v[234:237], v163 offset:39936
	global_load_lds_dwordx4 v[238:239], off
	v_lshl_add_u64 v[238:239], s[20:21], 0, v[134:135]
	s_mov_b32 m0, s27
	s_nop 0
	global_load_lds_dwordx4 v[238:239], off
	s_waitcnt vmcnt(8)
	s_waitcnt lgkmcnt(0)
	s_barrier
	s_setprio 1
	s_waitcnt lgkmcnt(0)
	v_mfma_f32_16x16x32_bf16 v[126:129], v[150:153], v[204:207], v[126:129]
	v_mfma_f32_16x16x32_bf16 v[122:125], v[168:171], v[204:207], v[122:125]
	v_mfma_f32_16x16x32_bf16 v[110:113], v[150:153], v[214:217], v[110:113]
	v_mfma_f32_16x16x32_bf16 v[106:109], v[168:171], v[214:217], v[106:109]
	v_mfma_f32_16x16x32_bf16 v[94:97], v[150:153], v[222:225], v[94:97]
	v_mfma_f32_16x16x32_bf16 v[90:93], v[168:171], v[222:225], v[90:93]
	v_mfma_f32_16x16x32_bf16 v[78:81], v[150:153], v[230:233], v[78:81]
	v_mfma_f32_16x16x32_bf16 v[74:77], v[168:171], v[230:233], v[74:77]
	v_mfma_f32_16x16x32_bf16 v[126:129], v[164:167], v[210:213], v[126:129]
	v_mfma_f32_16x16x32_bf16 v[122:125], v[172:175], v[210:213], v[122:125]
	v_mfma_f32_16x16x32_bf16 v[110:113], v[164:167], v[218:221], v[110:113]
	v_mfma_f32_16x16x32_bf16 v[106:109], v[172:175], v[218:221], v[106:109]
	v_mfma_f32_16x16x32_bf16 v[94:97], v[164:167], v[226:229], v[94:97]
	v_mfma_f32_16x16x32_bf16 v[90:93], v[172:175], v[226:229], v[90:93]
	v_mfma_f32_16x16x32_bf16 v[78:81], v[164:167], v[234:237], v[78:81]
	v_mfma_f32_16x16x32_bf16 v[74:77], v[172:175], v[234:237], v[74:77]
	s_setprio 0
	s_setprio 1
	v_mfma_f32_16x16x32_bf16 v[118:121], v[180:183], v[204:207], v[118:121]
	v_mfma_f32_16x16x32_bf16 v[114:117], v[196:199], v[204:207], v[114:117]
	v_mfma_f32_16x16x32_bf16 v[102:105], v[180:183], v[214:217], v[102:105]
	v_mfma_f32_16x16x32_bf16 v[98:101], v[196:199], v[214:217], v[98:101]
	v_mfma_f32_16x16x32_bf16 v[86:89], v[180:183], v[222:225], v[86:89]
	v_mfma_f32_16x16x32_bf16 v[82:85], v[196:199], v[222:225], v[82:85]
	v_mfma_f32_16x16x32_bf16 v[70:73], v[180:183], v[230:233], v[70:73]
	v_mfma_f32_16x16x32_bf16 v[66:69], v[196:199], v[230:233], v[66:69]
	v_mfma_f32_16x16x32_bf16 v[118:121], v[184:187], v[210:213], v[118:121]
	v_mfma_f32_16x16x32_bf16 v[114:117], v[200:203], v[210:213], v[114:117]
	v_mfma_f32_16x16x32_bf16 v[102:105], v[184:187], v[218:221], v[102:105]
	v_mfma_f32_16x16x32_bf16 v[98:101], v[200:203], v[218:221], v[98:101]
	v_mfma_f32_16x16x32_bf16 v[86:89], v[184:187], v[226:229], v[86:89]
	v_mfma_f32_16x16x32_bf16 v[82:85], v[200:203], v[226:229], v[82:85]
	v_mfma_f32_16x16x32_bf16 v[70:73], v[184:187], v[234:237], v[70:73]
	v_mfma_f32_16x16x32_bf16 v[66:69], v[200:203], v[234:237], v[66:69]
	s_setprio 0
	s_barrier
	s_add_i32 s20, s42, s23
	v_lshl_add_u64 v[154:155], v[154:155], 0, s[10:11]
	s_mov_b32 m0, s20
	ds_read_b128 v[204:207], v163 offset:49152
	ds_read_b128 v[210:213], v163 offset:50176
	ds_read_b128 v[214:217], v163 offset:51200
	ds_read_b128 v[218:221], v163 offset:52224
	ds_read_b128 v[222:225], v163 offset:53248
	ds_read_b128 v[226:229], v163 offset:54272
	ds_read_b128 v[230:233], v163 offset:55296
	ds_read_b128 v[234:237], v163 offset:56320
	global_load_lds_dwordx4 v[154:155], off
	s_add_i32 m0, s20, 0x2000
	s_add_u32 s18, s18, 0xb0080
	v_lshl_add_u64 v[154:155], v[176:177], 0, s[10:11]
	s_addc_u32 s19, s19, 0
	s_add_i32 s20, s43, s23
	global_load_lds_dwordx4 v[154:155], off
	v_lshl_add_u64 v[154:155], s[18:19], 0, v[132:133]
	s_mov_b32 m0, s20
	s_nop 0
	global_load_lds_dwordx4 v[154:155], off
	v_lshl_add_u64 v[154:155], s[18:19], 0, v[136:137]
	s_add_i32 m0, s20, 0x2000
	s_nop 0
	global_load_lds_dwordx4 v[154:155], off
	v_lshl_add_u64 v[154:155], v[188:189], 0, s[10:11]
	s_mov_b32 m0, s29
	s_nop 0
	global_load_lds_dwordx4 v[154:155], off
	v_lshl_add_u64 v[154:155], v[208:209], 0, s[10:11]
	s_mov_b32 m0, s30
	s_nop 0
	global_load_lds_dwordx4 v[154:155], off
	s_waitcnt vmcnt(8)
	s_waitcnt lgkmcnt(0)
	s_barrier
	s_setprio 1
	s_waitcnt lgkmcnt(0)
	v_mfma_f32_16x16x32_bf16 v[62:65], v[150:153], v[204:207], v[62:65]
	v_mfma_f32_16x16x32_bf16 v[58:61], v[168:171], v[204:207], v[58:61]
	v_mfma_f32_16x16x32_bf16 v[46:49], v[150:153], v[214:217], v[46:49]
	v_mfma_f32_16x16x32_bf16 v[42:45], v[168:171], v[214:217], v[42:45]
	v_mfma_f32_16x16x32_bf16 v[30:33], v[150:153], v[222:225], v[30:33]
	v_mfma_f32_16x16x32_bf16 v[26:29], v[168:171], v[222:225], v[26:29]
	v_mfma_f32_16x16x32_bf16 v[14:17], v[150:153], v[230:233], v[14:17]
	v_mfma_f32_16x16x32_bf16 v[10:13], v[168:171], v[230:233], v[10:13]
	v_mfma_f32_16x16x32_bf16 v[62:65], v[164:167], v[210:213], v[62:65]
	v_mfma_f32_16x16x32_bf16 v[58:61], v[172:175], v[210:213], v[58:61]
	v_mfma_f32_16x16x32_bf16 v[46:49], v[164:167], v[218:221], v[46:49]
	v_mfma_f32_16x16x32_bf16 v[42:45], v[172:175], v[218:221], v[42:45]
	v_mfma_f32_16x16x32_bf16 v[30:33], v[164:167], v[226:229], v[30:33]
	v_mfma_f32_16x16x32_bf16 v[26:29], v[172:175], v[226:229], v[26:29]
	v_mfma_f32_16x16x32_bf16 v[14:17], v[164:167], v[234:237], v[14:17]
	v_mfma_f32_16x16x32_bf16 v[10:13], v[172:175], v[234:237], v[10:13]
	s_setprio 0
	s_setprio 1
	v_mfma_f32_16x16x32_bf16 v[54:57], v[180:183], v[204:207], v[54:57]
	v_mfma_f32_16x16x32_bf16 v[50:53], v[196:199], v[204:207], v[50:53]
	v_mfma_f32_16x16x32_bf16 v[38:41], v[180:183], v[214:217], v[38:41]
	v_mfma_f32_16x16x32_bf16 v[34:37], v[196:199], v[214:217], v[34:37]
	v_mfma_f32_16x16x32_bf16 v[22:25], v[180:183], v[222:225], v[22:25]
	v_mfma_f32_16x16x32_bf16 v[18:21], v[196:199], v[222:225], v[18:21]
	v_mfma_f32_16x16x32_bf16 v[6:9], v[180:183], v[230:233], v[6:9]
	v_mfma_f32_16x16x32_bf16 v[2:5], v[196:199], v[230:233], v[2:5]
	v_mfma_f32_16x16x32_bf16 v[54:57], v[184:187], v[210:213], v[54:57]
	v_mfma_f32_16x16x32_bf16 v[50:53], v[200:203], v[210:213], v[50:53]
	v_mfma_f32_16x16x32_bf16 v[38:41], v[184:187], v[218:221], v[38:41]
	v_mfma_f32_16x16x32_bf16 v[34:37], v[200:203], v[218:221], v[34:37]
	v_mfma_f32_16x16x32_bf16 v[22:25], v[184:187], v[226:229], v[22:25]
	v_mfma_f32_16x16x32_bf16 v[18:21], v[200:203], v[226:229], v[18:21]
	v_mfma_f32_16x16x32_bf16 v[6:9], v[184:187], v[234:237], v[6:9]
	v_mfma_f32_16x16x32_bf16 v[2:5], v[200:203], v[234:237], v[2:5]
	s_setprio 0
	s_add_i32 s41, s41, 2
	s_add_u32 s16, s16, 0x100
	s_addc_u32 s17, s17, 0
	s_add_u32 s39, s39, 0x100
	s_addc_u32 s40, s40, 0
	s_cmp_gt_u32 s41, 41
	s_barrier
	s_cbranch_scc0 .LBB0_1652
	s_and_b64 vcc, exec, s[12:13]
	s_cbranch_vccz .LBB0_1655
	s_barrier
